# v92 + dupwait: the two remaining adjacent duplicate s_waitcnt dropped (strategy #1, redundant waits)
# speedup vs baseline: 1.0033x; 1.0001x over previous
.Ls4_nocp:
.LBB0_1012:
	v_lshl_or_b32 v224, s0, 7, v214
	v_and_b32_e32 v197, 64, v181
	v_add_u32_e32 v197, 64, v197
	s_nop 0
	v_ashrrev_i32_e32 v225, 31, v224
	s_waitcnt lgkmcnt(0)
	v_mov_b32_e32 v176, v174
	s_nop 0
	v_pk_mul_f32 v[142:143], v[142:143], v[176:177] op_sel_hi:[1,0]
	s_nop 0
	v_mul_f32_e32 v175, 0xbfb8aa3b, v142
	v_mul_f32_e32 v177, 0xbfb8aa3b, v143
	v_exp_f32_e32 v175, v175
	v_exp_f32_e32 v177, v177
	v_add_f32_e32 v175, 1.0, v175
	v_add_f32_e32 v177, 1.0, v177
	v_rcp_f32_e32 v226, v175
	v_rcp_f32_e32 v227, v177
	v_pk_mul_f32 v[144:145], v[144:145], v[176:177] op_sel_hi:[1,0]
	v_pk_mul_f32 v[138:139], v[138:139], v[176:177] op_sel_hi:[1,0]
	v_mul_f32_e32 v175, 0xbfb8aa3b, v144
	v_pk_mul_f32 v[142:143], v[142:143], v[226:227]
	v_exp_f32_e32 v175, v175
	v_pk_mul_f32 v[138:139], v[138:139], v[142:143]
	v_mul_f32_e32 v142, 0xbfb8aa3b, v145
	v_exp_f32_e32 v143, v142
	v_pk_mul_f32 v[134:135], v[134:135], v[176:177] op_sel_hi:[1,0]
	v_add_f32_e32 v142, 1.0, v175
	v_mul_f32_e32 v175, 0xbfb8aa3b, v134
	v_pk_mul_f32 v[140:141], v[140:141], v[176:177] op_sel_hi:[1,0]
	v_add_f32_e32 v143, 1.0, v143
	v_exp_f32_e32 v175, v175
	v_mul_f32_e32 v177, 0xbfb8aa3b, v135
	v_rcp_f32_e32 v142, v142
	v_exp_f32_e32 v177, v177
	v_rcp_f32_e32 v143, v143
	v_add_f32_e32 v175, 1.0, v175
	v_rcp_f32_e32 v226, v175
	v_add_f32_e32 v175, 1.0, v177
	v_pk_mul_f32 v[142:143], v[144:145], v[142:143]
	v_pk_mul_f32 v[136:137], v[136:137], v[176:177] op_sel_hi:[1,0]
	v_rcp_f32_e32 v227, v175
	v_pk_mul_f32 v[140:141], v[140:141], v[142:143]
	v_mul_f32_e32 v142, 0xbfb8aa3b, v136
	v_mul_f32_e32 v143, 0xbfb8aa3b, v137
	v_exp_f32_e32 v142, v142
	v_exp_f32_e32 v143, v143
	v_pk_mul_f32 v[130:131], v[130:131], v[176:177] op_sel_hi:[1,0]
	v_pk_mul_f32 v[134:135], v[134:135], v[226:227]
	v_pk_mul_f32 v[132:133], v[132:133], v[176:177] op_sel_hi:[1,0]
	v_pk_mul_f32 v[130:131], v[130:131], v[134:135]
	v_add_f32_e32 v134, 1.0, v142
	v_add_f32_e32 v135, 1.0, v143
	v_rcp_f32_e32 v134, v134
	v_rcp_f32_e32 v135, v135
	s_nop 0
	v_pk_mul_f32 v[134:135], v[136:137], v[134:135]
	s_nop 0
	v_pk_mul_f32 v[132:133], v[132:133], v[134:135]
	v_cvt_pk_bf16_f32 v134, v138, v139
	s_waitcnt lgkmcnt(0)
	v_cvt_pk_bf16_f32 v136, v130, v131
	v_cvt_pk_bf16_f32 v137, v132, v133
	v_mov_b64_e32 v[132:133], s[26:27]
	v_cvt_pk_bf16_f32 v135, v140, v141
	s_waitcnt lgkmcnt(0)
	v_mov_b32_e32 v138, v170
	v_mad_i64_i32 v[140:141], s[4:5], v210, s68, v[132:133]
	v_lshlrev_b64 v[130:131], 1, v[224:225]
	v_pk_mul_f32 v[126:127], v[126:127], v[138:139] op_sel_hi:[1,0]
	v_lshl_add_u64 v[140:141], v[140:141], 0, v[130:131]
	v_mul_f32_e32 v139, 0xbfb8aa3b, v126
	v_exp_f32_e32 v139, v139
	global_store_dwordx4 v[140:141], v[134:137], off
	v_pk_mul_f32 v[128:129], v[128:129], v[138:139] op_sel_hi:[1,0]
	s_nop 0
	v_mul_f32_e32 v134, 0xbfb8aa3b, v127
	v_exp_f32_e32 v135, v134
	v_mul_f32_e32 v136, 0xbfb8aa3b, v128
	v_mul_f32_e32 v137, 0xbfb8aa3b, v129
	v_exp_f32_e32 v136, v136
	v_exp_f32_e32 v137, v137
	v_add_f32_e32 v134, 1.0, v139
	v_add_f32_e32 v135, 1.0, v135
	v_rcp_f32_e32 v134, v134
	v_rcp_f32_e32 v135, v135
	v_add_f32_e32 v136, 1.0, v136
	v_add_f32_e32 v137, 1.0, v137
	v_rcp_f32_e32 v136, v136
	v_rcp_f32_e32 v137, v137
	v_pk_mul_f32 v[118:119], v[118:119], v[138:139] op_sel_hi:[1,0]
	v_pk_mul_f32 v[126:127], v[126:127], v[134:135]
	v_pk_mul_f32 v[120:121], v[120:121], v[138:139] op_sel_hi:[1,0]
	v_pk_mul_f32 v[118:119], v[118:119], v[126:127]
	v_pk_mul_f32 v[126:127], v[128:129], v[136:137]
	v_pk_mul_f32 v[122:123], v[122:123], v[138:139] op_sel_hi:[1,0]
	v_pk_mul_f32 v[120:121], v[120:121], v[126:127]
	v_mul_f32_e32 v128, 0xbfb8aa3b, v122
	v_mul_f32_e32 v126, 0xbfb8aa3b, v123
	v_exp_f32_e32 v128, v128
	v_exp_f32_e32 v127, v126
	v_pk_mul_f32 v[124:125], v[124:125], v[138:139] op_sel_hi:[1,0]
	v_pk_mul_f32 v[114:115], v[114:115], v[138:139] op_sel_hi:[1,0]
	v_add_f32_e32 v126, 1.0, v128
	v_add_f32_e32 v127, 1.0, v127
	v_mul_f32_e32 v128, 0xbfb8aa3b, v124
	v_mul_f32_e32 v129, 0xbfb8aa3b, v125
	v_rcp_f32_e32 v126, v126
	v_rcp_f32_e32 v127, v127
	v_exp_f32_e32 v128, v128
	v_exp_f32_e32 v129, v129
	v_pk_mul_f32 v[122:123], v[122:123], v[126:127]
	v_add_f32_e32 v126, 1.0, v128
	v_add_f32_e32 v127, 1.0, v129
	v_rcp_f32_e32 v126, v126
	v_rcp_f32_e32 v127, v127
	v_pk_mul_f32 v[122:123], v[114:115], v[122:123]
	v_pk_mul_f32 v[114:115], v[116:117], v[138:139] op_sel_hi:[1,0]
	v_pk_mul_f32 v[116:117], v[124:125], v[126:127]
	s_waitcnt lgkmcnt(0)
	v_pk_mul_f32 v[124:125], v[114:115], v[116:117]
	v_cvt_pk_bf16_f32 v114, v118, v119
	v_cvt_pk_bf16_f32 v115, v120, v121
	v_mad_i64_i32 v[120:121], s[4:5], v208, s68, v[132:133]
	s_waitcnt lgkmcnt(0)
	v_mov_b32_e32 v118, v166
	v_cvt_pk_bf16_f32 v116, v122, v123
	v_cvt_pk_bf16_f32 v117, v124, v125
	v_lshl_add_u64 v[120:121], v[120:121], 0, v[130:131]
	v_pk_mul_f32 v[110:111], v[110:111], v[118:119] op_sel_hi:[1,0]
	global_store_dwordx4 v[120:121], v[114:117], off
	v_mul_f32_e32 v119, 0xbfb8aa3b, v110
	v_exp_f32_e32 v119, v119
	v_mul_f32_e32 v114, 0xbfb8aa3b, v111
	v_exp_f32_e32 v115, v114
	v_pk_mul_f32 v[112:113], v[112:113], v[118:119] op_sel_hi:[1,0]
	s_nop 0
	v_mul_f32_e32 v116, 0xbfb8aa3b, v112
	v_mul_f32_e32 v117, 0xbfb8aa3b, v113
	v_exp_f32_e32 v116, v116
	v_exp_f32_e32 v117, v117
	v_add_f32_e32 v114, 1.0, v119
	v_add_f32_e32 v115, 1.0, v115
	v_rcp_f32_e32 v114, v114
	v_rcp_f32_e32 v115, v115
	v_add_f32_e32 v116, 1.0, v116
	v_add_f32_e32 v117, 1.0, v117
	v_rcp_f32_e32 v116, v116
	v_rcp_f32_e32 v117, v117
	v_pk_mul_f32 v[98:99], v[98:99], v[118:119] op_sel_hi:[1,0]
	v_pk_mul_f32 v[110:111], v[110:111], v[114:115]
	v_pk_mul_f32 v[100:101], v[100:101], v[118:119] op_sel_hi:[1,0]
	v_pk_mul_f32 v[98:99], v[98:99], v[110:111]
	v_pk_mul_f32 v[110:111], v[112:113], v[116:117]
	v_pk_mul_f32 v[102:103], v[102:103], v[118:119] op_sel_hi:[1,0]
	v_pk_mul_f32 v[100:101], v[100:101], v[110:111]
	v_mul_f32_e32 v112, 0xbfb8aa3b, v102
	v_mul_f32_e32 v110, 0xbfb8aa3b, v103
	v_exp_f32_e32 v112, v112
	v_exp_f32_e32 v111, v110
	v_pk_mul_f32 v[104:105], v[104:105], v[118:119] op_sel_hi:[1,0]
	v_pk_mul_f32 v[94:95], v[94:95], v[118:119] op_sel_hi:[1,0]
	v_add_f32_e32 v110, 1.0, v112
	v_add_f32_e32 v111, 1.0, v111
	v_mul_f32_e32 v112, 0xbfb8aa3b, v104
	v_mul_f32_e32 v113, 0xbfb8aa3b, v105
	v_rcp_f32_e32 v110, v110
	v_rcp_f32_e32 v111, v111
	v_exp_f32_e32 v112, v112
	v_exp_f32_e32 v113, v113
	v_pk_mul_f32 v[102:103], v[102:103], v[110:111]
	v_add_f32_e32 v110, 1.0, v112
	v_add_f32_e32 v111, 1.0, v113
	v_rcp_f32_e32 v110, v110
	v_rcp_f32_e32 v111, v111
	v_pk_mul_f32 v[102:103], v[94:95], v[102:103]
	v_pk_mul_f32 v[94:95], v[96:97], v[118:119] op_sel_hi:[1,0]
	v_pk_mul_f32 v[96:97], v[104:105], v[110:111]
	s_waitcnt lgkmcnt(0)
	v_pk_mul_f32 v[104:105], v[94:95], v[96:97]
	v_cvt_pk_bf16_f32 v94, v98, v99
	v_cvt_pk_bf16_f32 v95, v100, v101
	v_mad_i64_i32 v[100:101], s[4:5], v206, s68, v[132:133]
	s_waitcnt lgkmcnt(0)
	v_mov_b32_e32 v98, v162
	v_cvt_pk_bf16_f32 v96, v102, v103
	v_cvt_pk_bf16_f32 v97, v104, v105
	v_lshl_add_u64 v[100:101], v[100:101], 0, v[130:131]
	v_pk_mul_f32 v[90:91], v[90:91], v[98:99] op_sel_hi:[1,0]
	global_store_dwordx4 v[100:101], v[94:97], off
	v_mul_f32_e32 v99, 0xbfb8aa3b, v90
	v_exp_f32_e32 v99, v99
	v_mul_f32_e32 v94, 0xbfb8aa3b, v91
	v_exp_f32_e32 v95, v94
	v_pk_mul_f32 v[92:93], v[92:93], v[98:99] op_sel_hi:[1,0]
	s_nop 0
	v_mul_f32_e32 v96, 0xbfb8aa3b, v92
	v_mul_f32_e32 v97, 0xbfb8aa3b, v93
	v_exp_f32_e32 v96, v96
	v_exp_f32_e32 v97, v97
	v_add_f32_e32 v94, 1.0, v99
	v_add_f32_e32 v95, 1.0, v95
	v_rcp_f32_e32 v94, v94
	v_rcp_f32_e32 v95, v95
	v_add_f32_e32 v96, 1.0, v96
	v_add_f32_e32 v97, 1.0, v97
	v_rcp_f32_e32 v96, v96
	v_rcp_f32_e32 v97, v97
	v_pk_mul_f32 v[78:79], v[78:79], v[98:99] op_sel_hi:[1,0]
	v_pk_mul_f32 v[90:91], v[90:91], v[94:95]
	v_pk_mul_f32 v[82:83], v[82:83], v[98:99] op_sel_hi:[1,0]
	v_pk_mul_f32 v[78:79], v[78:79], v[90:91]
	v_pk_mul_f32 v[90:91], v[92:93], v[96:97]
	v_mul_f32_e32 v92, 0xbfb8aa3b, v82
	v_exp_f32_e32 v92, v92
	v_pk_mul_f32 v[80:81], v[80:81], v[98:99] op_sel_hi:[1,0]
	v_pk_mul_f32 v[84:85], v[84:85], v[98:99] op_sel_hi:[1,0]
	v_pk_mul_f32 v[80:81], v[80:81], v[90:91]
	v_mul_f32_e32 v90, 0xbfb8aa3b, v83
	v_exp_f32_e32 v91, v90
	v_add_f32_e32 v90, 1.0, v92
	v_mul_f32_e32 v92, 0xbfb8aa3b, v84
	v_mul_f32_e32 v93, 0xbfb8aa3b, v85
	v_exp_f32_e32 v92, v92
	v_exp_f32_e32 v93, v93
	v_add_f32_e32 v91, 1.0, v91
	v_rcp_f32_e32 v90, v90
	v_rcp_f32_e32 v91, v91
	v_add_f32_e32 v92, 1.0, v92
	v_add_f32_e32 v93, 1.0, v93
	v_rcp_f32_e32 v92, v92
	v_rcp_f32_e32 v93, v93
	v_pk_mul_f32 v[74:75], v[74:75], v[98:99] op_sel_hi:[1,0]
	v_pk_mul_f32 v[82:83], v[82:83], v[90:91]
	s_nop 0
	v_pk_mul_f32 v[82:83], v[74:75], v[82:83]
	v_pk_mul_f32 v[74:75], v[76:77], v[98:99] op_sel_hi:[1,0]
	v_pk_mul_f32 v[76:77], v[84:85], v[92:93]
	s_nop 0
	v_pk_mul_f32 v[84:85], v[74:75], v[76:77]
	v_cvt_pk_bf16_f32 v74, v78, v79
	v_mad_i64_i32 v[78:79], s[4:5], v204, s68, v[132:133]
	v_cvt_pk_bf16_f32 v75, v80, v81
	v_cvt_pk_bf16_f32 v76, v82, v83
	v_cvt_pk_bf16_f32 v77, v84, v85
	v_lshl_add_u64 v[78:79], v[78:79], 0, v[130:131]
	global_store_dwordx4 v[78:79], v[74:77], off
	s_mov_b64 s[100:101], s[6:7]
	s_andn2_b64 vcc, exec, s[6:7]
	s_cbranch_vccnz .LBB0_1030

.LBB0_1035:
	s_or_b64 exec, exec, s[6:7]
	s_nop 0
	s_waitcnt lgkmcnt(0)
	v_mov_b32_e32 v76, v106
	s_nop 0
	v_pk_mul_f32 v[62:63], v[62:63], v[76:77] op_sel_hi:[1,0]
	v_pk_mul_f32 v[58:59], v[58:59], v[76:77] op_sel_hi:[1,0]
	v_pk_mul_f32 v[64:65], v[64:65], v[76:77] op_sel_hi:[1,0]
	v_pk_mul_f32 v[60:61], v[60:61], v[76:77] op_sel_hi:[1,0]
	v_pk_mul_f32 v[54:55], v[54:55], v[76:77] op_sel_hi:[1,0]
	v_mul_f32_e32 v75, 0xbfb8aa3b, v62
	v_mul_f32_e32 v77, 0xbfb8aa3b, v63
	v_exp_f32_e32 v75, v75
	v_exp_f32_e32 v77, v77
	v_mul_f32_e32 v78, 0xbfb8aa3b, v64
	v_mul_f32_e32 v79, 0xbfb8aa3b, v65
	v_add_f32_e32 v75, 1.0, v75
	v_add_f32_e32 v77, 1.0, v77
	v_exp_f32_e32 v80, v78
	v_exp_f32_e32 v81, v79
	v_rcp_f32_e32 v78, v75
	v_rcp_f32_e32 v79, v77
	v_add_f32_e32 v75, 1.0, v80
	v_add_f32_e32 v77, 1.0, v81
	v_pk_mul_f32 v[56:57], v[56:57], v[76:77] op_sel_hi:[1,0]
	v_pk_mul_f32 v[62:63], v[62:63], v[78:79]
	v_pk_mul_f32 v[50:51], v[50:51], v[76:77] op_sel_hi:[1,0]
	v_pk_mul_f32 v[58:59], v[58:59], v[62:63]
	v_mul_f32_e32 v62, 0xbfb8aa3b, v54
	v_mul_f32_e32 v63, 0xbfb8aa3b, v55
	v_exp_f32_e32 v62, v62
	v_exp_f32_e32 v63, v63
	v_pk_mul_f32 v[52:53], v[52:53], v[76:77] op_sel_hi:[1,0]
	v_rcp_f32_e32 v80, v75
	v_add_f32_e32 v62, 1.0, v62
	v_add_f32_e32 v63, 1.0, v63
	v_rcp_f32_e32 v62, v62
	v_rcp_f32_e32 v63, v63
	v_rcp_f32_e32 v81, v77
	v_pk_mul_f32 v[54:55], v[54:55], v[62:63]
	v_mul_f32_e32 v62, 0xbfb8aa3b, v56
	v_mul_f32_e32 v63, 0xbfb8aa3b, v57
	v_exp_f32_e32 v62, v62
	v_exp_f32_e32 v63, v63
	v_pk_mul_f32 v[50:51], v[50:51], v[54:55]
	v_pk_mul_f32 v[64:65], v[64:65], v[80:81]
	v_add_f32_e32 v54, 1.0, v62
	v_add_f32_e32 v55, 1.0, v63
	v_rcp_f32_e32 v54, v54
	v_rcp_f32_e32 v55, v55
	v_pk_mul_f32 v[60:61], v[60:61], v[64:65]
	v_pk_mul_f32 v[54:55], v[56:57], v[54:55]
	s_nop 0
	v_pk_mul_f32 v[56:57], v[52:53], v[54:55]
	v_cvt_pk_bf16_f32 v52, v58, v59
	s_waitcnt lgkmcnt(0)
	v_cvt_pk_bf16_f32 v55, v56, v57
	v_cvt_pk_bf16_f32 v54, v50, v51
	v_mov_b64_e32 v[50:51], s[26:27]
	v_cvt_pk_bf16_f32 v53, v60, v61
	s_waitcnt lgkmcnt(0)
	v_mov_b32_e32 v56, v86
	v_mad_i64_i32 v[58:59], s[0:1], v202, s68, v[50:51]
	v_lshl_add_u64 v[58:59], v[58:59], 0, v[130:131]
	v_pk_mul_f32 v[46:47], v[46:47], v[56:57] op_sel_hi:[1,0]
	global_store_dwordx4 v[58:59], v[52:55], off
	v_mul_f32_e32 v57, 0xbfb8aa3b, v46
	v_exp_f32_e32 v57, v57
	v_mul_f32_e32 v52, 0xbfb8aa3b, v47
	v_exp_f32_e32 v53, v52
	v_pk_mul_f32 v[48:49], v[48:49], v[56:57] op_sel_hi:[1,0]
	s_nop 0
	v_mul_f32_e32 v54, 0xbfb8aa3b, v48
	v_mul_f32_e32 v55, 0xbfb8aa3b, v49
	v_exp_f32_e32 v54, v54
	v_exp_f32_e32 v55, v55
	v_add_f32_e32 v52, 1.0, v57
	v_add_f32_e32 v53, 1.0, v53
	v_rcp_f32_e32 v52, v52
	v_rcp_f32_e32 v53, v53
	v_add_f32_e32 v54, 1.0, v54
	v_add_f32_e32 v55, 1.0, v55
	v_rcp_f32_e32 v54, v54
	v_rcp_f32_e32 v55, v55
	v_pk_mul_f32 v[38:39], v[38:39], v[56:57] op_sel_hi:[1,0]
	v_pk_mul_f32 v[46:47], v[46:47], v[52:53]
	v_pk_mul_f32 v[40:41], v[40:41], v[56:57] op_sel_hi:[1,0]
	v_pk_mul_f32 v[38:39], v[38:39], v[46:47]
	v_pk_mul_f32 v[46:47], v[48:49], v[54:55]
	v_pk_mul_f32 v[42:43], v[42:43], v[56:57] op_sel_hi:[1,0]
	v_pk_mul_f32 v[40:41], v[40:41], v[46:47]
	v_mul_f32_e32 v48, 0xbfb8aa3b, v42
	v_mul_f32_e32 v46, 0xbfb8aa3b, v43
	v_exp_f32_e32 v48, v48
	v_exp_f32_e32 v47, v46
	v_pk_mul_f32 v[44:45], v[44:45], v[56:57] op_sel_hi:[1,0]
	v_pk_mul_f32 v[34:35], v[34:35], v[56:57] op_sel_hi:[1,0]
	v_add_f32_e32 v46, 1.0, v48
	v_add_f32_e32 v47, 1.0, v47
	v_mul_f32_e32 v48, 0xbfb8aa3b, v44
	v_mul_f32_e32 v49, 0xbfb8aa3b, v45
	v_rcp_f32_e32 v46, v46
	v_rcp_f32_e32 v47, v47
	v_exp_f32_e32 v48, v48
	v_exp_f32_e32 v49, v49
	v_pk_mul_f32 v[42:43], v[42:43], v[46:47]
	v_add_f32_e32 v46, 1.0, v48
	v_add_f32_e32 v47, 1.0, v49
	v_rcp_f32_e32 v46, v46
	v_rcp_f32_e32 v47, v47
	v_pk_mul_f32 v[42:43], v[34:35], v[42:43]
	v_pk_mul_f32 v[34:35], v[36:37], v[56:57] op_sel_hi:[1,0]
	v_pk_mul_f32 v[36:37], v[44:45], v[46:47]
	s_waitcnt lgkmcnt(0)
	v_pk_mul_f32 v[44:45], v[34:35], v[36:37]
	v_cvt_pk_bf16_f32 v34, v38, v39
	v_cvt_pk_bf16_f32 v35, v40, v41
	v_mad_i64_i32 v[40:41], s[0:1], v200, s68, v[50:51]
	s_waitcnt lgkmcnt(0)
	v_mov_b32_e32 v38, v70
	v_cvt_pk_bf16_f32 v36, v42, v43
	v_cvt_pk_bf16_f32 v37, v44, v45
	v_lshl_add_u64 v[40:41], v[40:41], 0, v[130:131]
	v_pk_mul_f32 v[30:31], v[30:31], v[38:39] op_sel_hi:[1,0]
	global_store_dwordx4 v[40:41], v[34:37], off
	v_mul_f32_e32 v39, 0xbfb8aa3b, v30
	v_exp_f32_e32 v39, v39
	v_mul_f32_e32 v34, 0xbfb8aa3b, v31
	v_exp_f32_e32 v35, v34
	v_pk_mul_f32 v[32:33], v[32:33], v[38:39] op_sel_hi:[1,0]
	s_nop 0
	v_mul_f32_e32 v36, 0xbfb8aa3b, v32
	v_mul_f32_e32 v37, 0xbfb8aa3b, v33
	v_exp_f32_e32 v36, v36
	v_exp_f32_e32 v37, v37
	v_add_f32_e32 v34, 1.0, v39
	v_add_f32_e32 v35, 1.0, v35
	v_rcp_f32_e32 v34, v34
	v_rcp_f32_e32 v35, v35
	v_add_f32_e32 v36, 1.0, v36
	v_add_f32_e32 v37, 1.0, v37
	v_rcp_f32_e32 v36, v36
	v_rcp_f32_e32 v37, v37
	v_pk_mul_f32 v[22:23], v[22:23], v[38:39] op_sel_hi:[1,0]
	v_pk_mul_f32 v[30:31], v[30:31], v[34:35]
	v_pk_mul_f32 v[24:25], v[24:25], v[38:39] op_sel_hi:[1,0]
	v_pk_mul_f32 v[22:23], v[22:23], v[30:31]
	v_pk_mul_f32 v[30:31], v[32:33], v[36:37]
	v_pk_mul_f32 v[26:27], v[26:27], v[38:39] op_sel_hi:[1,0]
	v_pk_mul_f32 v[24:25], v[24:25], v[30:31]
	v_mul_f32_e32 v32, 0xbfb8aa3b, v26
	v_mul_f32_e32 v30, 0xbfb8aa3b, v27
	v_exp_f32_e32 v32, v32
	v_exp_f32_e32 v31, v30
	v_pk_mul_f32 v[28:29], v[28:29], v[38:39] op_sel_hi:[1,0]
	v_pk_mul_f32 v[18:19], v[18:19], v[38:39] op_sel_hi:[1,0]
	v_add_f32_e32 v30, 1.0, v32
	v_add_f32_e32 v31, 1.0, v31
	v_mul_f32_e32 v32, 0xbfb8aa3b, v28
	v_mul_f32_e32 v33, 0xbfb8aa3b, v29
	v_rcp_f32_e32 v30, v30
	v_rcp_f32_e32 v31, v31
	v_exp_f32_e32 v32, v32
	v_exp_f32_e32 v33, v33
	v_pk_mul_f32 v[26:27], v[26:27], v[30:31]
	v_add_f32_e32 v30, 1.0, v32
	v_add_f32_e32 v31, 1.0, v33
	v_rcp_f32_e32 v30, v30
	v_rcp_f32_e32 v31, v31
	v_pk_mul_f32 v[26:27], v[18:19], v[26:27]
	v_pk_mul_f32 v[18:19], v[20:21], v[38:39] op_sel_hi:[1,0]
	v_pk_mul_f32 v[20:21], v[28:29], v[30:31]
	s_waitcnt lgkmcnt(0)
	v_pk_mul_f32 v[28:29], v[18:19], v[20:21]
	v_cvt_pk_bf16_f32 v18, v22, v23
	v_cvt_pk_bf16_f32 v19, v24, v25
	v_mad_i64_i32 v[24:25], s[0:1], v198, s68, v[50:51]
	s_waitcnt lgkmcnt(0)
	v_mov_b32_e32 v22, v66
	v_cvt_pk_bf16_f32 v20, v26, v27
	v_cvt_pk_bf16_f32 v21, v28, v29
	v_lshl_add_u64 v[24:25], v[24:25], 0, v[130:131]
	v_pk_mul_f32 v[14:15], v[14:15], v[22:23] op_sel_hi:[1,0]
	global_store_dwordx4 v[24:25], v[18:21], off
	v_mul_f32_e32 v23, 0xbfb8aa3b, v14
	v_exp_f32_e32 v23, v23
	v_mul_f32_e32 v18, 0xbfb8aa3b, v15
	v_exp_f32_e32 v19, v18
	v_pk_mul_f32 v[16:17], v[16:17], v[22:23] op_sel_hi:[1,0]
	s_nop 0
	v_mul_f32_e32 v20, 0xbfb8aa3b, v16
	v_mul_f32_e32 v21, 0xbfb8aa3b, v17
	v_exp_f32_e32 v20, v20
	v_exp_f32_e32 v21, v21
	v_add_f32_e32 v18, 1.0, v23
	v_add_f32_e32 v19, 1.0, v19
	v_rcp_f32_e32 v18, v18
	v_rcp_f32_e32 v19, v19
	v_add_f32_e32 v20, 1.0, v20
	v_add_f32_e32 v21, 1.0, v21
	v_rcp_f32_e32 v20, v20
	v_rcp_f32_e32 v21, v21
	v_pk_mul_f32 v[6:7], v[6:7], v[22:23] op_sel_hi:[1,0]
	v_pk_mul_f32 v[14:15], v[14:15], v[18:19]
	v_pk_mul_f32 v[10:11], v[10:11], v[22:23] op_sel_hi:[1,0]
	v_pk_mul_f32 v[6:7], v[6:7], v[14:15]
	v_pk_mul_f32 v[14:15], v[16:17], v[20:21]
	v_mul_f32_e32 v16, 0xbfb8aa3b, v10
	v_exp_f32_e32 v16, v16
	v_pk_mul_f32 v[8:9], v[8:9], v[22:23] op_sel_hi:[1,0]
	v_pk_mul_f32 v[12:13], v[12:13], v[22:23] op_sel_hi:[1,0]
	v_pk_mul_f32 v[8:9], v[8:9], v[14:15]
	v_mul_f32_e32 v14, 0xbfb8aa3b, v11
	v_exp_f32_e32 v15, v14
	v_add_f32_e32 v14, 1.0, v16
	v_mul_f32_e32 v16, 0xbfb8aa3b, v12
	v_mul_f32_e32 v17, 0xbfb8aa3b, v13
	v_exp_f32_e32 v16, v16
	v_exp_f32_e32 v17, v17
	v_add_f32_e32 v15, 1.0, v15
	v_rcp_f32_e32 v14, v14
	v_rcp_f32_e32 v15, v15
	v_add_f32_e32 v16, 1.0, v16
	v_add_f32_e32 v17, 1.0, v17
	v_rcp_f32_e32 v16, v16
	v_rcp_f32_e32 v17, v17
	v_pk_mul_f32 v[2:3], v[2:3], v[22:23] op_sel_hi:[1,0]
	v_pk_mul_f32 v[10:11], v[10:11], v[14:15]
	s_nop 0
	v_pk_mul_f32 v[10:11], v[2:3], v[10:11]
	v_pk_mul_f32 v[2:3], v[4:5], v[22:23] op_sel_hi:[1,0]
	v_pk_mul_f32 v[4:5], v[12:13], v[16:17]
	s_nop 0
	v_pk_mul_f32 v[12:13], v[2:3], v[4:5]
	v_cvt_pk_bf16_f32 v2, v6, v7
	v_mad_i64_i32 v[6:7], s[0:1], v196, s68, v[50:51]
	v_cvt_pk_bf16_f32 v3, v8, v9
	v_cvt_pk_bf16_f32 v4, v10, v11
	v_cvt_pk_bf16_f32 v5, v12, v13
	v_lshl_add_u64 v[6:7], v[6:7], 0, v[130:131]
	global_store_dwordx4 v[6:7], v[2:5], off
	s_and_saveexec_b64 s[6:7], s[80:81]
	s_cbranch_execz .LBB0_1037
	s_cmp_eq_u32 s98, 0
	s_cbranch_scc1 .Ls4dr_no
	s_waitcnt vmcnt(4)
	v_readfirstlane_b32 s0, v247
	s_nop 1
	v_add_u32_e32 v74, s0, v74
	v_min_u32_e32 v74, 0x8b7, v74
	v_add_u32_e32 v74, 0xc99, v74
